# phase 5 work queue reordered: nsa_prep items run before the short vtrans items (shorter phase tail)
# baseline (speedup 1.0000x reference)
; #define TIDX opaque_tid()
;     ...
;         while (true) {
;             const int it = fetch_item(ctl + 128 + l, lds);
;             if (it >= 640 + 640 + 512 + 256) break;
;             if (it < 640) { if (sub & 1) gdn_chunk(a, l, it, lds); }
;             else if (it < 1280) { if (sub & 2) hgrn_chunk(a, l, it - 640, lds); }
;             else if (it < 1792) { if (sub & 4) vtrans_item(a, it - 1280, lds); }
;             else { if (sub & 8) { for (int q = 0; q < 4; ++q) nsa_prep_token(a, (it - 1792) * 32 + q * 8 + (TIDX >> 6), TIDX & 63); } }
.LBB0_607:
	s_or_b64 exec, exec, s[2:3]
	s_mov_b64 s[2:3], src_shared_base
	s_add_i32 s2, 0, 0x22ff0
	s_cmp_lg_u32 s2, -1
	s_cselect_b32 s2, s2, 0
	s_cselect_b32 s3, s3, 0
	s_waitcnt lgkmcnt(0)
	s_barrier
	v_mov_b32_e32 v0, s2
	v_mov_b32_e32 v1, s3
	ds_read_b32 v0, v0
	s_mov_b64 s[2:3], -1
	s_waitcnt lgkmcnt(0)
	v_readfirstlane_b32 s50, v0
	s_cmpk_gt_i32 s50, 0x7ff
	s_cbranch_scc1 .LBB0_602
	s_cmpk_lt_u32 s50, 0x500
	s_cbranch_scc1 .Lp5_noswap
	s_cmpk_lt_u32 s50, 0x600
	s_cbranch_scc1 .Lp5_tonsa
	s_sub_u32 s50, s50, 0x100
	s_branch .Lp5_noswap
.Lp5_tonsa:
	s_add_u32 s50, s50, 0x200
.Lp5_noswap:
	s_cmpk_gt_i32 s50, 0x27f
	s_cbranch_scc0 .LBB0_634
	s_cmpk_gt_u32 s50, 0x4ff
	s_cbranch_scc0 .LBB0_625
	s_cmpk_lt_u32 s50, 0x700
	s_cbranch_scc1 .LBB0_622
	s_lshl_b32 s13, s50, 5
	s_add_i32 s13, s13, 0xffff2000
	s_mov_b32 s14, 0
	s_branch .LBB0_613
